# K-loop issue-slot trim: removed the 12 redundant mid-segment s_setprio 0/1 pairs between MFMA halves in the three GEMM K-loops
# baseline (speedup 1.0000x reference)
; #define PG8_STAGE(bufoff, gbase, voff) do { _Pragma("unroll") for (int _i = 0; _i < 2; ++_i) \
;         __builtin_amdgcn_global_load_lds((const unsigned*)((const char*)(gbase) + (voff)[_i]), (LAS unsigned*)(lds + (bufoff) + ldsw + _i * 8192), 16, 0, 0); } while (0)
; #define PG8_LDA(dst, b, h) do { _Pragma("unroll") for (int m = 0; m < 4; ++m) _Pragma("unroll") for (int k = 0; k < 2; ++k) dst[m][k] = *(const LAS bf16x8*)(lds + PG8_SA(b, h) + aoff + m * 2048 + k * 1024); } while (0)
; #define PG8_LDB(dst, b, h) do { _Pragma("unroll") for (int n = 0; n < 2; ++n) _Pragma("unroll") for (int k = 0; k < 2; ++k) dst[n][k] = *(const LAS bf16x8*)(lds + PG8_SB(b, h) + boff + n * 2048 + k * 1024); } while (0)
; #define PG8_MMA(ai, bj, At, Bt) do { __builtin_amdgcn_s_setprio(1); _Pragma("unroll") for (int m = 0; m < 4; ++m) _Pragma("unroll") for (int n = 0; n < 2; ++n) _Pragma("unroll") for (int k = 0; k < 2; ++k) \
;         acc[ai][bj][m][n] = __builtin_amdgcn_mfma_f32_16x16x32_bf16(Bt[n][k], At[m][k], acc[ai][bj][m][n], 0, 0, 0); __builtin_amdgcn_s_setprio(0); } while (0)
; #define PG8_WAIT_V(n) asm volatile("s_waitcnt vmcnt(" #n ")" ::: "memory")
; #define PG8_WAIT_L(n) asm volatile("s_waitcnt lgkmcnt(" #n ")" ::: "memory")
; #define PG8_BAR __builtin_amdgcn_s_barrier()
; #define PG8_SCHED __builtin_amdgcn_sched_barrier(0)
; template <class Epi, class Sched>
; __device__ __forceinline__ void gemm_phase(LAS unsigned char* lds, const int lda, const int ldb, const Sched& S, const Epi& E) {
;     ...
;             PG8_LDB(B0, 0, 0); PG8_LDB(B1, 0, 1); PG8_SCHED; PG8_LDA(At, 0, 0); PG8_STAGE(PG8_SA(1, 1), a1 + hstepA, voffA);
;             PG8_WAIT_V(8); PG8_WAIT_L(0); PG8_BAR; PG8_MMA(0, 0, At, B0); PG8_MMA(0, 1, At, B1); PG8_BAR; PG8_SCHED;
;             PG8_LDA(At, 0, 1); PG8_STAGE(PG8_SB(0, 0), b2, voffB); PG8_STAGE(PG8_SB(0, 1), b2 + hstepB, voffB); PG8_STAGE(PG8_SA(0, 0), a2, voffA);
;             PG8_WAIT_V(8); PG8_WAIT_L(0); PG8_BAR; PG8_MMA(1, 0, At, B0); PG8_MMA(1, 1, At, B1); PG8_BAR; PG8_SCHED;
.LBB0_206:
	s_add_u32 s36, s22, 0x100
	s_addc_u32 s37, s23, 0
	s_add_i32 s58, 0, 0x10000
	s_cmp_eq_u32 s38, 12
	s_cselect_b32 s47, s17, s37
	s_cselect_b32 s46, s16, s36
	s_cselect_b32 s45, s21, s25
	s_cselect_b32 s44, s20, s24
	s_add_i32 s59, 0, 0x14000
	v_add_u32_e32 v154, s58, v159
	v_add_u32_e32 v163, s59, v159
	ds_read_b128 v[142:145], v154
	ds_read_b128 v[146:149], v154 offset:1024
	ds_read_b128 v[150:153], v154 offset:2048
	ds_read_b128 v[154:157], v154 offset:3072
	ds_read_b128 v[164:167], v163
	ds_read_b128 v[168:171], v163 offset:1024
	ds_read_b128 v[172:175], v163 offset:2048
	ds_read_b128 v[176:179], v163 offset:3072
	v_lshl_add_u64 v[192:193], s[22:23], 0, v[138:139]
	s_add_i32 m0, s29, 0xc000
	ds_read_b128 v[180:183], v162
	ds_read_b128 v[184:187], v162 offset:1024
	ds_read_b128 v[188:191], v162 offset:2048
	ds_read_b128 v[206:209], v162 offset:3072
	ds_read_b128 v[210:213], v162 offset:4096
	ds_read_b128 v[214:217], v162 offset:5120
	ds_read_b128 v[218:221], v162 offset:6144
	ds_read_b128 v[222:225], v162 offset:7168
	global_load_lds_dwordx4 v[192:193], off
	v_lshl_add_u64 v[192:193], s[22:23], 0, v[140:141]
	s_add_i32 m0, s29, 0xe000
	s_nop 0
	global_load_lds_dwordx4 v[192:193], off
	s_waitcnt vmcnt(8)
	s_waitcnt lgkmcnt(0)
	s_barrier
	s_setprio 1
	s_waitcnt lgkmcnt(0)
	v_mfma_f32_16x16x32_bf16 v[126:129], v[142:145], v[180:183], v[126:129]
	v_mfma_f32_16x16x32_bf16 v[122:125], v[150:153], v[180:183], v[122:125]
	v_mfma_f32_16x16x32_bf16 v[118:121], v[142:145], v[188:191], v[118:121]
	v_mfma_f32_16x16x32_bf16 v[110:113], v[150:153], v[188:191], v[110:113]
	v_mfma_f32_16x16x32_bf16 v[102:105], v[142:145], v[210:213], v[102:105]
	v_mfma_f32_16x16x32_bf16 v[94:97], v[150:153], v[210:213], v[94:97]
	v_mfma_f32_16x16x32_bf16 v[86:89], v[142:145], v[218:221], v[86:89]
	v_mfma_f32_16x16x32_bf16 v[78:81], v[150:153], v[218:221], v[78:81]
	v_mfma_f32_16x16x32_bf16 v[126:129], v[146:149], v[184:187], v[126:129]
	v_mfma_f32_16x16x32_bf16 v[122:125], v[154:157], v[184:187], v[122:125]
	v_mfma_f32_16x16x32_bf16 v[118:121], v[146:149], v[206:209], v[118:121]
	v_mfma_f32_16x16x32_bf16 v[110:113], v[154:157], v[206:209], v[110:113]
	v_mfma_f32_16x16x32_bf16 v[102:105], v[146:149], v[214:217], v[102:105]
	v_mfma_f32_16x16x32_bf16 v[94:97], v[154:157], v[214:217], v[94:97]
	v_mfma_f32_16x16x32_bf16 v[86:89], v[146:149], v[222:225], v[86:89]
	v_mfma_f32_16x16x32_bf16 v[78:81], v[154:157], v[222:225], v[78:81]
	v_mfma_f32_16x16x32_bf16 v[114:117], v[164:167], v[180:183], v[114:117]
	v_mfma_f32_16x16x32_bf16 v[106:109], v[172:175], v[180:183], v[106:109]
	v_mfma_f32_16x16x32_bf16 v[98:101], v[164:167], v[188:191], v[98:101]
	v_mfma_f32_16x16x32_bf16 v[90:93], v[172:175], v[188:191], v[90:93]
	v_mfma_f32_16x16x32_bf16 v[82:85], v[164:167], v[210:213], v[82:85]
	v_mfma_f32_16x16x32_bf16 v[74:77], v[172:175], v[210:213], v[74:77]
	v_mfma_f32_16x16x32_bf16 v[70:73], v[164:167], v[218:221], v[70:73]
	v_mfma_f32_16x16x32_bf16 v[66:69], v[172:175], v[218:221], v[66:69]
	v_mfma_f32_16x16x32_bf16 v[114:117], v[168:171], v[184:187], v[114:117]
	v_mfma_f32_16x16x32_bf16 v[106:109], v[176:179], v[184:187], v[106:109]
	v_mfma_f32_16x16x32_bf16 v[98:101], v[168:171], v[206:209], v[98:101]
	v_mfma_f32_16x16x32_bf16 v[90:93], v[176:179], v[206:209], v[90:93]
	v_mfma_f32_16x16x32_bf16 v[82:85], v[168:171], v[214:217], v[82:85]
	v_mfma_f32_16x16x32_bf16 v[74:77], v[176:179], v[214:217], v[74:77]
	v_mfma_f32_16x16x32_bf16 v[70:73], v[168:171], v[222:225], v[70:73]
	v_mfma_f32_16x16x32_bf16 v[66:69], v[176:179], v[222:225], v[66:69]
	s_setprio 0
	s_barrier
	s_add_i32 s22, s58, s26
	v_lshl_add_u64 v[192:193], s[44:45], 0, v[134:135]
	s_mov_b32 m0, s22
	ds_read_b128 v[180:183], v162 offset:16384
	ds_read_b128 v[184:187], v162 offset:17408
	ds_read_b128 v[188:191], v162 offset:18432
	ds_read_b128 v[206:209], v162 offset:19456
	ds_read_b128 v[210:213], v162 offset:20480
	ds_read_b128 v[214:217], v162 offset:21504
	ds_read_b128 v[218:221], v162 offset:22528
	ds_read_b128 v[222:225], v162 offset:23552
	global_load_lds_dwordx4 v[192:193], off
	s_add_i32 m0, s22, 0x2000
	s_add_u32 s22, s44, 0x40000
	v_lshl_add_u64 v[240:241], s[44:45], 0, v[130:131]
	s_addc_u32 s23, s45, 0
	s_add_i32 s58, s59, s26
	global_load_lds_dwordx4 v[240:241], off
	v_lshl_add_u64 v[242:243], s[22:23], 0, v[134:135]
	s_mov_b32 m0, s58
	v_lshl_add_u64 v[244:245], s[46:47], 0, v[132:133]
	global_load_lds_dwordx4 v[242:243], off
	v_lshl_add_u64 v[242:243], s[22:23], 0, v[130:131]
	s_add_i32 m0, s58, 0x2000
	s_nop 0
	global_load_lds_dwordx4 v[242:243], off
	v_lshl_add_u64 v[242:243], s[46:47], 0, v[136:137]
	s_mov_b32 m0, s29
	s_nop 0
	global_load_lds_dwordx4 v[242:243], off
	s_mov_b32 m0, s33
	s_nop 0
	global_load_lds_dwordx4 v[244:245], off
	s_waitcnt vmcnt(8)
	s_waitcnt lgkmcnt(0)
	s_barrier
; #define PG8_STAGE(bufoff, gbase, voff) do { _Pragma("unroll") for (int _i = 0; _i < 2; ++_i) \
;         __builtin_amdgcn_global_load_lds((const unsigned*)((const char*)(gbase) + (voff)[_i]), (LAS unsigned*)(lds + (bufoff) + ldsw + _i * 8192), 16, 0, 0); } while (0)
; #define PG8_LDA(dst, b, h) do { _Pragma("unroll") for (int m = 0; m < 4; ++m) _Pragma("unroll") for (int k = 0; k < 2; ++k) dst[m][k] = *(const LAS bf16x8*)(lds + PG8_SA(b, h) + aoff + m * 2048 + k * 1024); } while (0)
; #define PG8_LDB(dst, b, h) do { _Pragma("unroll") for (int n = 0; n < 2; ++n) _Pragma("unroll") for (int k = 0; k < 2; ++k) dst[n][k] = *(const LAS bf16x8*)(lds + PG8_SB(b, h) + boff + n * 2048 + k * 1024); } while (0)
; #define PG8_MMA(ai, bj, At, Bt) do { __builtin_amdgcn_s_setprio(1); _Pragma("unroll") for (int m = 0; m < 4; ++m) _Pragma("unroll") for (int n = 0; n < 2; ++n) _Pragma("unroll") for (int k = 0; k < 2; ++k) \
;         acc[ai][bj][m][n] = __builtin_amdgcn_mfma_f32_16x16x32_bf16(Bt[n][k], At[m][k], acc[ai][bj][m][n], 0, 0, 0); __builtin_amdgcn_s_setprio(0); } while (0)
; #define PG8_WAIT_V(n) asm volatile("s_waitcnt vmcnt(" #n ")" ::: "memory")
; #define PG8_WAIT_L(n) asm volatile("s_waitcnt lgkmcnt(" #n ")" ::: "memory")
; #define PG8_BAR __builtin_amdgcn_s_barrier()
; #define PG8_SCHED __builtin_amdgcn_sched_barrier(0)
; template <class Epi, class Sched>
; __device__ __forceinline__ void gemm_phase(LAS unsigned char* lds, const int lda, const int ldb, const Sched& S, const Epi& E) {
;     ...
;             PG8_WAIT_V(8); PG8_WAIT_L(0); PG8_BAR; PG8_MMA(1, 0, At, B0); PG8_MMA(1, 1, At, B1); PG8_BAR; PG8_SCHED;
;             PG8_LDB(B0, 1, 0); PG8_LDB(B1, 1, 1); PG8_SCHED; PG8_LDA(At, 1, 0); PG8_STAGE(PG8_SA(0, 1), a2 + hstepA, voffA);
;             PG8_WAIT_V(8); PG8_WAIT_L(0); PG8_BAR; PG8_MMA(0, 0, At, B0); PG8_MMA(0, 1, At, B1); PG8_BAR; PG8_SCHED;
	s_setprio 1
	s_waitcnt lgkmcnt(0)
	v_mfma_f32_16x16x32_bf16 v[62:65], v[142:145], v[180:183], v[62:65]
	v_mfma_f32_16x16x32_bf16 v[58:61], v[150:153], v[180:183], v[58:61]
	v_mfma_f32_16x16x32_bf16 v[54:57], v[142:145], v[188:191], v[54:57]
	v_mfma_f32_16x16x32_bf16 v[46:49], v[150:153], v[188:191], v[46:49]
	v_mfma_f32_16x16x32_bf16 v[38:41], v[142:145], v[210:213], v[38:41]
	v_mfma_f32_16x16x32_bf16 v[30:33], v[150:153], v[210:213], v[30:33]
	v_mfma_f32_16x16x32_bf16 v[22:25], v[142:145], v[218:221], v[22:25]
	v_mfma_f32_16x16x32_bf16 v[14:17], v[150:153], v[218:221], v[14:17]
	v_mfma_f32_16x16x32_bf16 v[62:65], v[146:149], v[184:187], v[62:65]
	v_mfma_f32_16x16x32_bf16 v[58:61], v[154:157], v[184:187], v[58:61]
	v_mfma_f32_16x16x32_bf16 v[54:57], v[146:149], v[206:209], v[54:57]
	v_mfma_f32_16x16x32_bf16 v[46:49], v[154:157], v[206:209], v[46:49]
	v_mfma_f32_16x16x32_bf16 v[38:41], v[146:149], v[214:217], v[38:41]
	v_mfma_f32_16x16x32_bf16 v[30:33], v[154:157], v[214:217], v[30:33]
	v_mfma_f32_16x16x32_bf16 v[22:25], v[146:149], v[222:225], v[22:25]
	v_mfma_f32_16x16x32_bf16 v[14:17], v[154:157], v[222:225], v[14:17]
	v_mfma_f32_16x16x32_bf16 v[50:53], v[164:167], v[180:183], v[50:53]
	v_mfma_f32_16x16x32_bf16 v[42:45], v[172:175], v[180:183], v[42:45]
	v_mfma_f32_16x16x32_bf16 v[34:37], v[164:167], v[188:191], v[34:37]
	v_mfma_f32_16x16x32_bf16 v[26:29], v[172:175], v[188:191], v[26:29]
	v_mfma_f32_16x16x32_bf16 v[18:21], v[164:167], v[210:213], v[18:21]
	v_mfma_f32_16x16x32_bf16 v[10:13], v[172:175], v[210:213], v[10:13]
	v_mfma_f32_16x16x32_bf16 v[6:9], v[164:167], v[218:221], v[6:9]
	v_mfma_f32_16x16x32_bf16 v[2:5], v[172:175], v[218:221], v[2:5]
	v_mfma_f32_16x16x32_bf16 v[50:53], v[168:171], v[184:187], v[50:53]
	v_mfma_f32_16x16x32_bf16 v[42:45], v[176:179], v[184:187], v[42:45]
	v_mfma_f32_16x16x32_bf16 v[34:37], v[168:171], v[206:209], v[34:37]
	v_mfma_f32_16x16x32_bf16 v[26:29], v[176:179], v[206:209], v[26:29]
	v_mfma_f32_16x16x32_bf16 v[18:21], v[168:171], v[214:217], v[18:21]
	v_mfma_f32_16x16x32_bf16 v[10:13], v[176:179], v[214:217], v[10:13]
	v_mfma_f32_16x16x32_bf16 v[6:9], v[168:171], v[222:225], v[6:9]
	v_mfma_f32_16x16x32_bf16 v[2:5], v[176:179], v[222:225], v[2:5]
	s_setprio 0
	s_barrier
	s_add_i32 s58, 0, 0x18000
	s_add_i32 s59, 0, 0x1c000
	v_add_u32_e32 v154, s58, v159
	v_add_u32_e32 v163, s59, v159
	ds_read_b128 v[142:145], v154
	ds_read_b128 v[146:149], v154 offset:1024
	ds_read_b128 v[150:153], v154 offset:2048
	ds_read_b128 v[154:157], v154 offset:3072
	ds_read_b128 v[164:167], v163
	ds_read_b128 v[168:171], v163 offset:1024
	ds_read_b128 v[172:175], v163 offset:2048
	ds_read_b128 v[176:179], v163 offset:3072
	s_add_u32 s22, s46, 0x190000
	s_addc_u32 s23, s47, 0
	s_mov_b32 m0, s48
	v_lshl_add_u64 v[246:247], s[22:23], 0, v[136:137]
	ds_read_b128 v[180:183], v162 offset:32768
	ds_read_b128 v[184:187], v162 offset:33792
	ds_read_b128 v[188:191], v162 offset:34816
	ds_read_b128 v[206:209], v162 offset:35840
	ds_read_b128 v[210:213], v162 offset:36864
	ds_read_b128 v[214:217], v162 offset:37888
	ds_read_b128 v[218:221], v162 offset:38912
	ds_read_b128 v[222:225], v162 offset:39936
	global_load_lds_dwordx4 v[246:247], off
	v_lshl_add_u64 v[246:247], s[22:23], 0, v[132:133]
	s_mov_b32 m0, s49
	s_nop 0
	global_load_lds_dwordx4 v[246:247], off
	s_waitcnt vmcnt(8)
	s_waitcnt lgkmcnt(0)
	s_barrier
	s_setprio 1
	s_waitcnt lgkmcnt(0)
	v_mfma_f32_16x16x32_bf16 v[126:129], v[142:145], v[180:183], v[126:129]
	v_mfma_f32_16x16x32_bf16 v[122:125], v[150:153], v[180:183], v[122:125]
	v_mfma_f32_16x16x32_bf16 v[118:121], v[142:145], v[188:191], v[118:121]
	v_mfma_f32_16x16x32_bf16 v[110:113], v[150:153], v[188:191], v[110:113]
	v_mfma_f32_16x16x32_bf16 v[102:105], v[142:145], v[210:213], v[102:105]
	v_mfma_f32_16x16x32_bf16 v[94:97], v[150:153], v[210:213], v[94:97]
	v_mfma_f32_16x16x32_bf16 v[86:89], v[142:145], v[218:221], v[86:89]
	v_mfma_f32_16x16x32_bf16 v[78:81], v[150:153], v[218:221], v[78:81]
	v_mfma_f32_16x16x32_bf16 v[126:129], v[146:149], v[184:187], v[126:129]
	v_mfma_f32_16x16x32_bf16 v[122:125], v[154:157], v[184:187], v[122:125]
	v_mfma_f32_16x16x32_bf16 v[118:121], v[146:149], v[206:209], v[118:121]
	v_mfma_f32_16x16x32_bf16 v[110:113], v[154:157], v[206:209], v[110:113]
	v_mfma_f32_16x16x32_bf16 v[102:105], v[146:149], v[214:217], v[102:105]
	v_mfma_f32_16x16x32_bf16 v[94:97], v[154:157], v[214:217], v[94:97]
	v_mfma_f32_16x16x32_bf16 v[86:89], v[146:149], v[222:225], v[86:89]
	v_mfma_f32_16x16x32_bf16 v[78:81], v[154:157], v[222:225], v[78:81]
	v_mfma_f32_16x16x32_bf16 v[114:117], v[164:167], v[180:183], v[114:117]
	v_mfma_f32_16x16x32_bf16 v[106:109], v[172:175], v[180:183], v[106:109]
	v_mfma_f32_16x16x32_bf16 v[98:101], v[164:167], v[188:191], v[98:101]
	v_mfma_f32_16x16x32_bf16 v[90:93], v[172:175], v[188:191], v[90:93]
	v_mfma_f32_16x16x32_bf16 v[82:85], v[164:167], v[210:213], v[82:85]
	v_mfma_f32_16x16x32_bf16 v[74:77], v[172:175], v[210:213], v[74:77]
	v_mfma_f32_16x16x32_bf16 v[70:73], v[164:167], v[218:221], v[70:73]
	v_mfma_f32_16x16x32_bf16 v[66:69], v[172:175], v[218:221], v[66:69]
	v_mfma_f32_16x16x32_bf16 v[114:117], v[168:171], v[184:187], v[114:117]
	v_mfma_f32_16x16x32_bf16 v[106:109], v[176:179], v[184:187], v[106:109]
	v_mfma_f32_16x16x32_bf16 v[98:101], v[168:171], v[206:209], v[98:101]
	v_mfma_f32_16x16x32_bf16 v[90:93], v[176:179], v[206:209], v[90:93]
	v_mfma_f32_16x16x32_bf16 v[82:85], v[168:171], v[214:217], v[82:85]
	v_mfma_f32_16x16x32_bf16 v[74:77], v[176:179], v[214:217], v[74:77]
	v_mfma_f32_16x16x32_bf16 v[70:73], v[168:171], v[222:225], v[70:73]
	v_mfma_f32_16x16x32_bf16 v[66:69], v[176:179], v[222:225], v[66:69]
	s_setprio 0
	s_barrier
; #define PG8_STAGE(bufoff, gbase, voff) do { _Pragma("unroll") for (int _i = 0; _i < 2; ++_i) \
;         __builtin_amdgcn_global_load_lds((const unsigned*)((const char*)(gbase) + (voff)[_i]), (LAS unsigned*)(lds + (bufoff) + ldsw + _i * 8192), 16, 0, 0); } while (0)
; #define PG8_LDA(dst, b, h) do { _Pragma("unroll") for (int m = 0; m < 4; ++m) _Pragma("unroll") for (int k = 0; k < 2; ++k) dst[m][k] = *(const LAS bf16x8*)(lds + PG8_SA(b, h) + aoff + m * 2048 + k * 1024); } while (0)
; #define PG8_MMA(ai, bj, At, Bt) do { __builtin_amdgcn_s_setprio(1); _Pragma("unroll") for (int m = 0; m < 4; ++m) _Pragma("unroll") for (int n = 0; n < 2; ++n) _Pragma("unroll") for (int k = 0; k < 2; ++k) \
;         acc[ai][bj][m][n] = __builtin_amdgcn_mfma_f32_16x16x32_bf16(Bt[n][k], At[m][k], acc[ai][bj][m][n], 0, 0, 0); __builtin_amdgcn_s_setprio(0); } while (0)
; #define PG8_WAIT_V(n) asm volatile("s_waitcnt vmcnt(" #n ")" ::: "memory")
; #define PG8_WAIT_L(n) asm volatile("s_waitcnt lgkmcnt(" #n ")" ::: "memory")
; #define PG8_BAR __builtin_amdgcn_s_barrier()
; #define PG8_SCHED __builtin_amdgcn_sched_barrier(0)
; template <class Epi, class Sched>
; __device__ __forceinline__ void gemm_phase(LAS unsigned char* lds, const int lda, const int ldb, const Sched& S, const Epi& E) {
;     ...
;             PG8_LDA(At, 1, 1); PG8_STAGE(PG8_SB(1, 0), b3, voffB); PG8_STAGE(PG8_SB(1, 1), b3 + hstepB, voffB); PG8_STAGE(PG8_SA(1, 0), a3, voffA);
;             PG8_WAIT_V(8); PG8_WAIT_L(0); PG8_BAR; PG8_MMA(1, 0, At, B0); PG8_MMA(1, 1, At, B1); PG8_BAR; PG8_SCHED;
;         }
;         if (wr == 0) PG8_BAR;
	s_add_i32 s22, s58, s26
	v_lshl_add_u64 v[192:193], v[192:193], 0, s[82:83]
	s_mov_b32 m0, s22
	ds_read_b128 v[180:183], v162 offset:49152
	ds_read_b128 v[184:187], v162 offset:50176
	ds_read_b128 v[188:191], v162 offset:51200
	ds_read_b128 v[206:209], v162 offset:52224
	ds_read_b128 v[210:213], v162 offset:53248
	ds_read_b128 v[214:217], v162 offset:54272
	ds_read_b128 v[218:221], v162 offset:55296
	ds_read_b128 v[222:225], v162 offset:56320
	global_load_lds_dwordx4 v[192:193], off
	s_add_i32 m0, s22, 0x2000
	s_add_u32 s22, s44, 0x40080
	v_lshl_add_u64 v[192:193], v[240:241], 0, s[82:83]
	s_addc_u32 s23, s45, 0
	s_add_i32 s44, s59, s26
	global_load_lds_dwordx4 v[192:193], off
	v_lshl_add_u64 v[192:193], s[22:23], 0, v[134:135]
	s_mov_b32 m0, s44
	s_nop 0
	global_load_lds_dwordx4 v[192:193], off
	v_lshl_add_u64 v[192:193], s[22:23], 0, v[130:131]
	s_add_i32 m0, s44, 0x2000
	s_nop 0
	global_load_lds_dwordx4 v[192:193], off
	v_lshl_add_u64 v[192:193], v[242:243], 0, s[82:83]
	s_mov_b32 m0, s50
	s_nop 0
	global_load_lds_dwordx4 v[192:193], off
	v_lshl_add_u64 v[192:193], v[244:245], 0, s[82:83]
	s_mov_b32 m0, s51
	s_nop 0
	global_load_lds_dwordx4 v[192:193], off
	s_waitcnt vmcnt(8)
	s_waitcnt lgkmcnt(0)
	s_barrier
	s_setprio 1
	s_waitcnt lgkmcnt(0)
	v_mfma_f32_16x16x32_bf16 v[62:65], v[142:145], v[180:183], v[62:65]
	v_mfma_f32_16x16x32_bf16 v[58:61], v[150:153], v[180:183], v[58:61]
	v_mfma_f32_16x16x32_bf16 v[54:57], v[142:145], v[188:191], v[54:57]
	v_mfma_f32_16x16x32_bf16 v[46:49], v[150:153], v[188:191], v[46:49]
	v_mfma_f32_16x16x32_bf16 v[38:41], v[142:145], v[210:213], v[38:41]
	v_mfma_f32_16x16x32_bf16 v[30:33], v[150:153], v[210:213], v[30:33]
	v_mfma_f32_16x16x32_bf16 v[22:25], v[142:145], v[218:221], v[22:25]
	v_mfma_f32_16x16x32_bf16 v[14:17], v[150:153], v[218:221], v[14:17]
	v_mfma_f32_16x16x32_bf16 v[62:65], v[146:149], v[184:187], v[62:65]
	v_mfma_f32_16x16x32_bf16 v[58:61], v[154:157], v[184:187], v[58:61]
	v_mfma_f32_16x16x32_bf16 v[54:57], v[146:149], v[206:209], v[54:57]
	v_mfma_f32_16x16x32_bf16 v[46:49], v[154:157], v[206:209], v[46:49]
	v_mfma_f32_16x16x32_bf16 v[38:41], v[146:149], v[214:217], v[38:41]
	v_mfma_f32_16x16x32_bf16 v[30:33], v[154:157], v[214:217], v[30:33]
	v_mfma_f32_16x16x32_bf16 v[22:25], v[146:149], v[222:225], v[22:25]
	v_mfma_f32_16x16x32_bf16 v[14:17], v[154:157], v[222:225], v[14:17]
	v_mfma_f32_16x16x32_bf16 v[50:53], v[164:167], v[180:183], v[50:53]
	v_mfma_f32_16x16x32_bf16 v[42:45], v[172:175], v[180:183], v[42:45]
	v_mfma_f32_16x16x32_bf16 v[34:37], v[164:167], v[188:191], v[34:37]
	v_mfma_f32_16x16x32_bf16 v[26:29], v[172:175], v[188:191], v[26:29]
	v_mfma_f32_16x16x32_bf16 v[18:21], v[164:167], v[210:213], v[18:21]
	v_mfma_f32_16x16x32_bf16 v[10:13], v[172:175], v[210:213], v[10:13]
	v_mfma_f32_16x16x32_bf16 v[6:9], v[164:167], v[218:221], v[6:9]
	v_mfma_f32_16x16x32_bf16 v[2:5], v[172:175], v[218:221], v[2:5]
	v_mfma_f32_16x16x32_bf16 v[50:53], v[168:171], v[184:187], v[50:53]
	v_mfma_f32_16x16x32_bf16 v[42:45], v[176:179], v[184:187], v[42:45]
	v_mfma_f32_16x16x32_bf16 v[34:37], v[168:171], v[206:209], v[34:37]
	v_mfma_f32_16x16x32_bf16 v[26:29], v[176:179], v[206:209], v[26:29]
	v_mfma_f32_16x16x32_bf16 v[18:21], v[168:171], v[214:217], v[18:21]
	v_mfma_f32_16x16x32_bf16 v[10:13], v[176:179], v[214:217], v[10:13]
	v_mfma_f32_16x16x32_bf16 v[6:9], v[168:171], v[222:225], v[6:9]
	v_mfma_f32_16x16x32_bf16 v[2:5], v[176:179], v[222:225], v[2:5]
	s_setprio 0
	s_barrier
	s_add_i32 s38, s38, 2
	s_add_u32 s24, s24, 0x100
	s_addc_u32 s25, s25, 0
	s_cmp_gt_u32 s38, 13
	s_mov_b64 s[22:23], s[36:37]
	s_cbranch_scc0 .LBB0_206
	s_and_b64 vcc, exec, s[10:11]
	s_cbranch_vccz .LBB0_209
	s_barrier

; #define PG8_STAGE(bufoff, gbase, voff) do { _Pragma("unroll") for (int _i = 0; _i < 2; ++_i) \
;         __builtin_amdgcn_global_load_lds((const unsigned*)((const char*)(gbase) + (voff)[_i]), (LAS unsigned*)(lds + (bufoff) + ldsw + _i * 8192), 16, 0, 0); } while (0)
; #define PG8_LDA(dst, b, h) do { _Pragma("unroll") for (int m = 0; m < 4; ++m) _Pragma("unroll") for (int k = 0; k < 2; ++k) dst[m][k] = *(const LAS bf16x8*)(lds + PG8_SA(b, h) + aoff + m * 2048 + k * 1024); } while (0)
; #define PG8_LDB(dst, b, h) do { _Pragma("unroll") for (int n = 0; n < 2; ++n) _Pragma("unroll") for (int k = 0; k < 2; ++k) dst[n][k] = *(const LAS bf16x8*)(lds + PG8_SB(b, h) + boff + n * 2048 + k * 1024); } while (0)
; #define PG8_MMA(ai, bj, At, Bt) do { __builtin_amdgcn_s_setprio(1); _Pragma("unroll") for (int m = 0; m < 4; ++m) _Pragma("unroll") for (int n = 0; n < 2; ++n) _Pragma("unroll") for (int k = 0; k < 2; ++k) \
;         acc[ai][bj][m][n] = __builtin_amdgcn_mfma_f32_16x16x32_bf16(Bt[n][k], At[m][k], acc[ai][bj][m][n], 0, 0, 0); __builtin_amdgcn_s_setprio(0); } while (0)
; #define PG8_WAIT_V(n) asm volatile("s_waitcnt vmcnt(" #n ")" ::: "memory")
; #define PG8_WAIT_L(n) asm volatile("s_waitcnt lgkmcnt(" #n ")" ::: "memory")
; #define PG8_BAR __builtin_amdgcn_s_barrier()
; #define PG8_SCHED __builtin_amdgcn_sched_barrier(0)
; template <class Epi, class Sched>
; __device__ __forceinline__ void gemm_phase(LAS unsigned char* lds, const int lda, const int ldb, const Sched& S, const Epi& E) {
;     ...
;             PG8_LDB(B0, 0, 0); PG8_LDB(B1, 0, 1); PG8_SCHED; PG8_LDA(At, 0, 0); PG8_STAGE(PG8_SA(1, 1), a1 + hstepA, voffA);
;             PG8_WAIT_V(8); PG8_WAIT_L(0); PG8_BAR; PG8_MMA(0, 0, At, B0); PG8_MMA(0, 1, At, B1); PG8_BAR; PG8_SCHED;
;             PG8_LDA(At, 0, 1); PG8_STAGE(PG8_SB(0, 0), b2, voffB); PG8_STAGE(PG8_SB(0, 1), b2 + hstepB, voffB); PG8_STAGE(PG8_SA(0, 0), a2, voffA);
;             PG8_WAIT_V(8); PG8_WAIT_L(0); PG8_BAR; PG8_MMA(1, 0, At, B0); PG8_MMA(1, 1, At, B1); PG8_BAR; PG8_SCHED;
.LBB0_662:
	s_add_i32 s61, s44, 2
	s_add_u32 s36, s22, 0x100
	s_addc_u32 s37, s23, 0
	s_add_i32 s62, 0, 0x10000
	s_cmp_eq_u32 s24, s44
	s_cselect_b32 s47, s19, s37
	s_cselect_b32 s46, s18, s36
	s_cselect_b32 s45, s21, s60
	s_cselect_b32 s44, s20, s25
	s_add_i32 s63, 0, 0x14000
	v_add_u32_e32 v142, s62, v241
	v_add_u32_e32 v158, s63, v241
	ds_read_b128 v[130:133], v142
	ds_read_b128 v[134:137], v142 offset:1024
	ds_read_b128 v[138:141], v142 offset:2048
	ds_read_b128 v[142:145], v142 offset:3072
	ds_read_b128 v[146:149], v158
	ds_read_b128 v[150:153], v158 offset:1024
	ds_read_b128 v[154:157], v158 offset:2048
	ds_read_b128 v[158:161], v158 offset:3072
	v_lshl_add_u64 v[216:217], s[22:23], 0, v[212:213]
	s_add_i32 m0, s27, 0xc000
	ds_read_b128 v[162:165], v244
	ds_read_b128 v[166:169], v244 offset:1024
	ds_read_b128 v[170:173], v244 offset:2048
	ds_read_b128 v[174:177], v244 offset:3072
	ds_read_b128 v[178:181], v244 offset:4096
	ds_read_b128 v[182:185], v244 offset:5120
	ds_read_b128 v[186:189], v244 offset:6144
	ds_read_b128 v[190:193], v244 offset:7168
	global_load_lds_dwordx4 v[216:217], off
	v_lshl_add_u64 v[216:217], s[22:23], 0, v[214:215]
	s_add_i32 m0, s27, 0xe000
	s_nop 0
	global_load_lds_dwordx4 v[216:217], off
	s_waitcnt vmcnt(8)
	s_waitcnt lgkmcnt(0)
	s_barrier
	s_setprio 1
	s_waitcnt lgkmcnt(0)
	v_mfma_f32_16x16x32_bf16 v[126:129], v[130:133], v[162:165], v[126:129]
	v_mfma_f32_16x16x32_bf16 v[122:125], v[138:141], v[162:165], v[122:125]
	v_mfma_f32_16x16x32_bf16 v[110:113], v[130:133], v[170:173], v[110:113]
	v_mfma_f32_16x16x32_bf16 v[106:109], v[138:141], v[170:173], v[106:109]
	v_mfma_f32_16x16x32_bf16 v[94:97], v[130:133], v[178:181], v[94:97]
	v_mfma_f32_16x16x32_bf16 v[90:93], v[138:141], v[178:181], v[90:93]
	v_mfma_f32_16x16x32_bf16 v[78:81], v[130:133], v[186:189], v[78:81]
	v_mfma_f32_16x16x32_bf16 v[74:77], v[138:141], v[186:189], v[74:77]
	v_mfma_f32_16x16x32_bf16 v[126:129], v[134:137], v[166:169], v[126:129]
	v_mfma_f32_16x16x32_bf16 v[122:125], v[142:145], v[166:169], v[122:125]
	v_mfma_f32_16x16x32_bf16 v[110:113], v[134:137], v[174:177], v[110:113]
	v_mfma_f32_16x16x32_bf16 v[106:109], v[142:145], v[174:177], v[106:109]
	v_mfma_f32_16x16x32_bf16 v[94:97], v[134:137], v[182:185], v[94:97]
	v_mfma_f32_16x16x32_bf16 v[90:93], v[142:145], v[182:185], v[90:93]
	v_mfma_f32_16x16x32_bf16 v[78:81], v[134:137], v[190:193], v[78:81]
	v_mfma_f32_16x16x32_bf16 v[74:77], v[142:145], v[190:193], v[74:77]
	v_mfma_f32_16x16x32_bf16 v[118:121], v[146:149], v[162:165], v[118:121]
	v_mfma_f32_16x16x32_bf16 v[114:117], v[154:157], v[162:165], v[114:117]
	v_mfma_f32_16x16x32_bf16 v[102:105], v[146:149], v[170:173], v[102:105]
	v_mfma_f32_16x16x32_bf16 v[98:101], v[154:157], v[170:173], v[98:101]
	v_mfma_f32_16x16x32_bf16 v[86:89], v[146:149], v[178:181], v[86:89]
	v_mfma_f32_16x16x32_bf16 v[82:85], v[154:157], v[178:181], v[82:85]
	v_mfma_f32_16x16x32_bf16 v[70:73], v[146:149], v[186:189], v[70:73]
	v_mfma_f32_16x16x32_bf16 v[66:69], v[154:157], v[186:189], v[66:69]
	v_mfma_f32_16x16x32_bf16 v[118:121], v[150:153], v[166:169], v[118:121]
	v_mfma_f32_16x16x32_bf16 v[114:117], v[158:161], v[166:169], v[114:117]
	v_mfma_f32_16x16x32_bf16 v[102:105], v[150:153], v[174:177], v[102:105]
	v_mfma_f32_16x16x32_bf16 v[98:101], v[158:161], v[174:177], v[98:101]
	v_mfma_f32_16x16x32_bf16 v[86:89], v[150:153], v[182:185], v[86:89]
	v_mfma_f32_16x16x32_bf16 v[82:85], v[158:161], v[182:185], v[82:85]
	v_mfma_f32_16x16x32_bf16 v[70:73], v[150:153], v[190:193], v[70:73]
	v_mfma_f32_16x16x32_bf16 v[66:69], v[158:161], v[190:193], v[66:69]
	s_setprio 0
	s_barrier
	s_add_i32 s22, s62, s26
	v_lshl_add_u64 v[216:217], s[44:45], 0, v[0:1]
	s_mov_b32 m0, s22
	ds_read_b128 v[162:165], v244 offset:16384
	ds_read_b128 v[166:169], v244 offset:17408
	ds_read_b128 v[170:173], v244 offset:18432
	ds_read_b128 v[174:177], v244 offset:19456
	ds_read_b128 v[178:181], v244 offset:20480
	ds_read_b128 v[182:185], v244 offset:21504
	ds_read_b128 v[186:189], v244 offset:22528
	ds_read_b128 v[190:193], v244 offset:23552
	global_load_lds_dwordx4 v[216:217], off
	s_add_i32 m0, s22, 0x2000
	s_add_u32 s22, s44, 0x40000
	v_lshl_add_u64 v[218:219], s[44:45], 0, v[210:211]
	s_addc_u32 s23, s45, 0
	s_add_i32 s62, s63, s26
	global_load_lds_dwordx4 v[218:219], off
	v_lshl_add_u64 v[220:221], s[22:23], 0, v[0:1]
	s_mov_b32 m0, s62
	v_lshl_add_u64 v[222:223], s[46:47], 0, v[208:209]
	global_load_lds_dwordx4 v[220:221], off
	v_lshl_add_u64 v[220:221], s[22:23], 0, v[210:211]
	s_add_i32 m0, s62, 0x2000
	s_nop 0
	global_load_lds_dwordx4 v[220:221], off
	v_lshl_add_u64 v[220:221], s[46:47], 0, v[206:207]
	s_mov_b32 m0, s27
	s_nop 0
	global_load_lds_dwordx4 v[220:221], off
	s_mov_b32 m0, s28
	s_nop 0
	global_load_lds_dwordx4 v[222:223], off
	s_waitcnt vmcnt(8)
	s_waitcnt lgkmcnt(0)
	s_barrier
; #define PG8_STAGE(bufoff, gbase, voff) do { _Pragma("unroll") for (int _i = 0; _i < 2; ++_i) \
;         __builtin_amdgcn_global_load_lds((const unsigned*)((const char*)(gbase) + (voff)[_i]), (LAS unsigned*)(lds + (bufoff) + ldsw + _i * 8192), 16, 0, 0); } while (0)
; #define PG8_LDA(dst, b, h) do { _Pragma("unroll") for (int m = 0; m < 4; ++m) _Pragma("unroll") for (int k = 0; k < 2; ++k) dst[m][k] = *(const LAS bf16x8*)(lds + PG8_SA(b, h) + aoff + m * 2048 + k * 1024); } while (0)
; #define PG8_LDB(dst, b, h) do { _Pragma("unroll") for (int n = 0; n < 2; ++n) _Pragma("unroll") for (int k = 0; k < 2; ++k) dst[n][k] = *(const LAS bf16x8*)(lds + PG8_SB(b, h) + boff + n * 2048 + k * 1024); } while (0)
; #define PG8_MMA(ai, bj, At, Bt) do { __builtin_amdgcn_s_setprio(1); _Pragma("unroll") for (int m = 0; m < 4; ++m) _Pragma("unroll") for (int n = 0; n < 2; ++n) _Pragma("unroll") for (int k = 0; k < 2; ++k) \
;         acc[ai][bj][m][n] = __builtin_amdgcn_mfma_f32_16x16x32_bf16(Bt[n][k], At[m][k], acc[ai][bj][m][n], 0, 0, 0); __builtin_amdgcn_s_setprio(0); } while (0)
; #define PG8_WAIT_V(n) asm volatile("s_waitcnt vmcnt(" #n ")" ::: "memory")
; #define PG8_WAIT_L(n) asm volatile("s_waitcnt lgkmcnt(" #n ")" ::: "memory")
; #define PG8_BAR __builtin_amdgcn_s_barrier()
; #define PG8_SCHED __builtin_amdgcn_sched_barrier(0)
; template <class Epi, class Sched>
; __device__ __forceinline__ void gemm_phase(LAS unsigned char* lds, const int lda, const int ldb, const Sched& S, const Epi& E) {
;     ...
;             PG8_WAIT_V(8); PG8_WAIT_L(0); PG8_BAR; PG8_MMA(1, 0, At, B0); PG8_MMA(1, 1, At, B1); PG8_BAR; PG8_SCHED;
;             PG8_LDB(B0, 1, 0); PG8_LDB(B1, 1, 1); PG8_SCHED; PG8_LDA(At, 1, 0); PG8_STAGE(PG8_SA(0, 1), a2 + hstepA, voffA);
;             PG8_WAIT_V(8); PG8_WAIT_L(0); PG8_BAR; PG8_MMA(0, 0, At, B0); PG8_MMA(0, 1, At, B1); PG8_BAR; PG8_SCHED;
	s_setprio 1
	s_waitcnt lgkmcnt(0)
	v_mfma_f32_16x16x32_bf16 v[62:65], v[130:133], v[162:165], v[62:65]
	v_mfma_f32_16x16x32_bf16 v[58:61], v[138:141], v[162:165], v[58:61]
	v_mfma_f32_16x16x32_bf16 v[46:49], v[130:133], v[170:173], v[46:49]
	v_mfma_f32_16x16x32_bf16 v[42:45], v[138:141], v[170:173], v[42:45]
	v_mfma_f32_16x16x32_bf16 v[30:33], v[130:133], v[178:181], v[30:33]
	v_mfma_f32_16x16x32_bf16 v[26:29], v[138:141], v[178:181], v[26:29]
	v_mfma_f32_16x16x32_bf16 v[14:17], v[130:133], v[186:189], v[14:17]
	v_mfma_f32_16x16x32_bf16 v[10:13], v[138:141], v[186:189], v[10:13]
	v_mfma_f32_16x16x32_bf16 v[62:65], v[134:137], v[166:169], v[62:65]
	v_mfma_f32_16x16x32_bf16 v[58:61], v[142:145], v[166:169], v[58:61]
	v_mfma_f32_16x16x32_bf16 v[46:49], v[134:137], v[174:177], v[46:49]
	v_mfma_f32_16x16x32_bf16 v[42:45], v[142:145], v[174:177], v[42:45]
	v_mfma_f32_16x16x32_bf16 v[30:33], v[134:137], v[182:185], v[30:33]
	v_mfma_f32_16x16x32_bf16 v[26:29], v[142:145], v[182:185], v[26:29]
	v_mfma_f32_16x16x32_bf16 v[14:17], v[134:137], v[190:193], v[14:17]
	v_mfma_f32_16x16x32_bf16 v[10:13], v[142:145], v[190:193], v[10:13]
	v_mfma_f32_16x16x32_bf16 v[54:57], v[146:149], v[162:165], v[54:57]
	v_mfma_f32_16x16x32_bf16 v[50:53], v[154:157], v[162:165], v[50:53]
	v_mfma_f32_16x16x32_bf16 v[38:41], v[146:149], v[170:173], v[38:41]
	v_mfma_f32_16x16x32_bf16 v[34:37], v[154:157], v[170:173], v[34:37]
	v_mfma_f32_16x16x32_bf16 v[22:25], v[146:149], v[178:181], v[22:25]
	v_mfma_f32_16x16x32_bf16 v[18:21], v[154:157], v[178:181], v[18:21]
	v_mfma_f32_16x16x32_bf16 v[6:9], v[146:149], v[186:189], v[6:9]
	v_mfma_f32_16x16x32_bf16 v[2:5], v[154:157], v[186:189], v[2:5]
	v_mfma_f32_16x16x32_bf16 v[54:57], v[150:153], v[166:169], v[54:57]
	v_mfma_f32_16x16x32_bf16 v[50:53], v[158:161], v[166:169], v[50:53]
	v_mfma_f32_16x16x32_bf16 v[38:41], v[150:153], v[174:177], v[38:41]
	v_mfma_f32_16x16x32_bf16 v[34:37], v[158:161], v[174:177], v[34:37]
	v_mfma_f32_16x16x32_bf16 v[22:25], v[150:153], v[182:185], v[22:25]
	v_mfma_f32_16x16x32_bf16 v[18:21], v[158:161], v[182:185], v[18:21]
	v_mfma_f32_16x16x32_bf16 v[6:9], v[150:153], v[190:193], v[6:9]
	v_mfma_f32_16x16x32_bf16 v[2:5], v[158:161], v[190:193], v[2:5]
	s_setprio 0
	s_barrier
	s_add_i32 s62, 0, 0x18000
	s_add_i32 s63, 0, 0x1c000
	v_add_u32_e32 v142, s62, v241
	v_add_u32_e32 v158, s63, v241
	ds_read_b128 v[130:133], v142
	ds_read_b128 v[134:137], v142 offset:1024
	ds_read_b128 v[138:141], v142 offset:2048
	ds_read_b128 v[142:145], v142 offset:3072
	ds_read_b128 v[146:149], v158
	ds_read_b128 v[150:153], v158 offset:1024
	ds_read_b128 v[154:157], v158 offset:2048
	ds_read_b128 v[158:161], v158 offset:3072
	s_add_u32 s22, s46, 0x190000
	s_addc_u32 s23, s47, 0
	s_mov_b32 m0, s29
	v_lshl_add_u64 v[224:225], s[22:23], 0, v[206:207]
	ds_read_b128 v[162:165], v244 offset:32768
	ds_read_b128 v[166:169], v244 offset:33792
	ds_read_b128 v[170:173], v244 offset:34816
	ds_read_b128 v[174:177], v244 offset:35840
	ds_read_b128 v[178:181], v244 offset:36864
	ds_read_b128 v[182:185], v244 offset:37888
	ds_read_b128 v[186:189], v244 offset:38912
	ds_read_b128 v[190:193], v244 offset:39936
	global_load_lds_dwordx4 v[224:225], off
	v_lshl_add_u64 v[224:225], s[22:23], 0, v[208:209]
	s_mov_b32 m0, s33
	s_nop 0
	global_load_lds_dwordx4 v[224:225], off
	s_waitcnt vmcnt(8)
	s_waitcnt lgkmcnt(0)
	s_barrier
	s_setprio 1
	s_waitcnt lgkmcnt(0)
	v_mfma_f32_16x16x32_bf16 v[126:129], v[130:133], v[162:165], v[126:129]
	v_mfma_f32_16x16x32_bf16 v[122:125], v[138:141], v[162:165], v[122:125]
	v_mfma_f32_16x16x32_bf16 v[110:113], v[130:133], v[170:173], v[110:113]
	v_mfma_f32_16x16x32_bf16 v[106:109], v[138:141], v[170:173], v[106:109]
	v_mfma_f32_16x16x32_bf16 v[94:97], v[130:133], v[178:181], v[94:97]
	v_mfma_f32_16x16x32_bf16 v[90:93], v[138:141], v[178:181], v[90:93]
	v_mfma_f32_16x16x32_bf16 v[78:81], v[130:133], v[186:189], v[78:81]
	v_mfma_f32_16x16x32_bf16 v[74:77], v[138:141], v[186:189], v[74:77]
	v_mfma_f32_16x16x32_bf16 v[126:129], v[134:137], v[166:169], v[126:129]
	v_mfma_f32_16x16x32_bf16 v[122:125], v[142:145], v[166:169], v[122:125]
	v_mfma_f32_16x16x32_bf16 v[110:113], v[134:137], v[174:177], v[110:113]
	v_mfma_f32_16x16x32_bf16 v[106:109], v[142:145], v[174:177], v[106:109]
	v_mfma_f32_16x16x32_bf16 v[94:97], v[134:137], v[182:185], v[94:97]
	v_mfma_f32_16x16x32_bf16 v[90:93], v[142:145], v[182:185], v[90:93]
	v_mfma_f32_16x16x32_bf16 v[78:81], v[134:137], v[190:193], v[78:81]
	v_mfma_f32_16x16x32_bf16 v[74:77], v[142:145], v[190:193], v[74:77]
	v_mfma_f32_16x16x32_bf16 v[118:121], v[146:149], v[162:165], v[118:121]
	v_mfma_f32_16x16x32_bf16 v[114:117], v[154:157], v[162:165], v[114:117]
	v_mfma_f32_16x16x32_bf16 v[102:105], v[146:149], v[170:173], v[102:105]
	v_mfma_f32_16x16x32_bf16 v[98:101], v[154:157], v[170:173], v[98:101]
	v_mfma_f32_16x16x32_bf16 v[86:89], v[146:149], v[178:181], v[86:89]
	v_mfma_f32_16x16x32_bf16 v[82:85], v[154:157], v[178:181], v[82:85]
	v_mfma_f32_16x16x32_bf16 v[70:73], v[146:149], v[186:189], v[70:73]
	v_mfma_f32_16x16x32_bf16 v[66:69], v[154:157], v[186:189], v[66:69]
	v_mfma_f32_16x16x32_bf16 v[118:121], v[150:153], v[166:169], v[118:121]
	v_mfma_f32_16x16x32_bf16 v[114:117], v[158:161], v[166:169], v[114:117]
	v_mfma_f32_16x16x32_bf16 v[102:105], v[150:153], v[174:177], v[102:105]
	v_mfma_f32_16x16x32_bf16 v[98:101], v[158:161], v[174:177], v[98:101]
	v_mfma_f32_16x16x32_bf16 v[86:89], v[150:153], v[182:185], v[86:89]
	v_mfma_f32_16x16x32_bf16 v[82:85], v[158:161], v[182:185], v[82:85]
	v_mfma_f32_16x16x32_bf16 v[70:73], v[150:153], v[190:193], v[70:73]
	v_mfma_f32_16x16x32_bf16 v[66:69], v[158:161], v[190:193], v[66:69]
	s_setprio 0
	s_barrier
; #define PG8_STAGE(bufoff, gbase, voff) do { _Pragma("unroll") for (int _i = 0; _i < 2; ++_i) \
;         __builtin_amdgcn_global_load_lds((const unsigned*)((const char*)(gbase) + (voff)[_i]), (LAS unsigned*)(lds + (bufoff) + ldsw + _i * 8192), 16, 0, 0); } while (0)
; #define PG8_LDA(dst, b, h) do { _Pragma("unroll") for (int m = 0; m < 4; ++m) _Pragma("unroll") for (int k = 0; k < 2; ++k) dst[m][k] = *(const LAS bf16x8*)(lds + PG8_SA(b, h) + aoff + m * 2048 + k * 1024); } while (0)
; #define PG8_MMA(ai, bj, At, Bt) do { __builtin_amdgcn_s_setprio(1); _Pragma("unroll") for (int m = 0; m < 4; ++m) _Pragma("unroll") for (int n = 0; n < 2; ++n) _Pragma("unroll") for (int k = 0; k < 2; ++k) \
;         acc[ai][bj][m][n] = __builtin_amdgcn_mfma_f32_16x16x32_bf16(Bt[n][k], At[m][k], acc[ai][bj][m][n], 0, 0, 0); __builtin_amdgcn_s_setprio(0); } while (0)
; #define PG8_WAIT_V(n) asm volatile("s_waitcnt vmcnt(" #n ")" ::: "memory")
; #define PG8_WAIT_L(n) asm volatile("s_waitcnt lgkmcnt(" #n ")" ::: "memory")
; #define PG8_BAR __builtin_amdgcn_s_barrier()
; #define PG8_SCHED __builtin_amdgcn_sched_barrier(0)
; template <class Epi, class Sched>
; __device__ __forceinline__ void gemm_phase(LAS unsigned char* lds, const int lda, const int ldb, const Sched& S, const Epi& E) {
;     ...
;             PG8_LDA(At, 1, 1); PG8_STAGE(PG8_SB(1, 0), b3, voffB); PG8_STAGE(PG8_SB(1, 1), b3 + hstepB, voffB); PG8_STAGE(PG8_SA(1, 0), a3, voffA);
;             PG8_WAIT_V(8); PG8_WAIT_L(0); PG8_BAR; PG8_MMA(1, 0, At, B0); PG8_MMA(1, 1, At, B1); PG8_BAR; PG8_SCHED;
;         }
;         if (wr == 0) PG8_BAR;
	s_add_i32 s22, s62, s26
	v_lshl_add_u64 v[216:217], v[216:217], 0, s[82:83]
	s_mov_b32 m0, s22
	ds_read_b128 v[162:165], v244 offset:49152
	ds_read_b128 v[166:169], v244 offset:50176
	ds_read_b128 v[170:173], v244 offset:51200
	ds_read_b128 v[174:177], v244 offset:52224
	ds_read_b128 v[178:181], v244 offset:53248
	ds_read_b128 v[182:185], v244 offset:54272
	ds_read_b128 v[186:189], v244 offset:55296
	ds_read_b128 v[190:193], v244 offset:56320
	global_load_lds_dwordx4 v[216:217], off
	s_add_i32 m0, s22, 0x2000
	s_add_u32 s22, s44, 0x40080
	v_lshl_add_u64 v[216:217], v[218:219], 0, s[82:83]
	s_addc_u32 s23, s45, 0
	s_add_i32 s44, s63, s26
	global_load_lds_dwordx4 v[216:217], off
	v_lshl_add_u64 v[216:217], s[22:23], 0, v[0:1]
	s_mov_b32 m0, s44
	s_nop 0
	global_load_lds_dwordx4 v[216:217], off
	v_lshl_add_u64 v[216:217], s[22:23], 0, v[210:211]
	s_add_i32 m0, s44, 0x2000
	s_nop 0
	global_load_lds_dwordx4 v[216:217], off
	v_lshl_add_u64 v[216:217], v[220:221], 0, s[82:83]
	s_mov_b32 m0, s38
	s_nop 0
	global_load_lds_dwordx4 v[216:217], off
	v_lshl_add_u64 v[216:217], v[222:223], 0, s[82:83]
	s_mov_b32 m0, s48
	s_nop 0
	global_load_lds_dwordx4 v[216:217], off
	s_waitcnt vmcnt(8)
	s_waitcnt lgkmcnt(0)
	s_barrier
	s_setprio 1
	s_waitcnt lgkmcnt(0)
	v_mfma_f32_16x16x32_bf16 v[62:65], v[130:133], v[162:165], v[62:65]
	v_mfma_f32_16x16x32_bf16 v[58:61], v[138:141], v[162:165], v[58:61]
	v_mfma_f32_16x16x32_bf16 v[46:49], v[130:133], v[170:173], v[46:49]
	v_mfma_f32_16x16x32_bf16 v[42:45], v[138:141], v[170:173], v[42:45]
	v_mfma_f32_16x16x32_bf16 v[30:33], v[130:133], v[178:181], v[30:33]
	v_mfma_f32_16x16x32_bf16 v[26:29], v[138:141], v[178:181], v[26:29]
	v_mfma_f32_16x16x32_bf16 v[14:17], v[130:133], v[186:189], v[14:17]
	v_mfma_f32_16x16x32_bf16 v[10:13], v[138:141], v[186:189], v[10:13]
	v_mfma_f32_16x16x32_bf16 v[62:65], v[134:137], v[166:169], v[62:65]
	v_mfma_f32_16x16x32_bf16 v[58:61], v[142:145], v[166:169], v[58:61]
	v_mfma_f32_16x16x32_bf16 v[46:49], v[134:137], v[174:177], v[46:49]
	v_mfma_f32_16x16x32_bf16 v[42:45], v[142:145], v[174:177], v[42:45]
	v_mfma_f32_16x16x32_bf16 v[30:33], v[134:137], v[182:185], v[30:33]
	v_mfma_f32_16x16x32_bf16 v[26:29], v[142:145], v[182:185], v[26:29]
	v_mfma_f32_16x16x32_bf16 v[14:17], v[134:137], v[190:193], v[14:17]
	v_mfma_f32_16x16x32_bf16 v[10:13], v[142:145], v[190:193], v[10:13]
	v_mfma_f32_16x16x32_bf16 v[54:57], v[146:149], v[162:165], v[54:57]
	v_mfma_f32_16x16x32_bf16 v[50:53], v[154:157], v[162:165], v[50:53]
	v_mfma_f32_16x16x32_bf16 v[38:41], v[146:149], v[170:173], v[38:41]
	v_mfma_f32_16x16x32_bf16 v[34:37], v[154:157], v[170:173], v[34:37]
	v_mfma_f32_16x16x32_bf16 v[22:25], v[146:149], v[178:181], v[22:25]
	v_mfma_f32_16x16x32_bf16 v[18:21], v[154:157], v[178:181], v[18:21]
	v_mfma_f32_16x16x32_bf16 v[6:9], v[146:149], v[186:189], v[6:9]
	v_mfma_f32_16x16x32_bf16 v[2:5], v[154:157], v[186:189], v[2:5]
	v_mfma_f32_16x16x32_bf16 v[54:57], v[150:153], v[166:169], v[54:57]
	v_mfma_f32_16x16x32_bf16 v[50:53], v[158:161], v[166:169], v[50:53]
	v_mfma_f32_16x16x32_bf16 v[38:41], v[150:153], v[174:177], v[38:41]
	v_mfma_f32_16x16x32_bf16 v[34:37], v[158:161], v[174:177], v[34:37]
	v_mfma_f32_16x16x32_bf16 v[22:25], v[150:153], v[182:185], v[22:25]
	v_mfma_f32_16x16x32_bf16 v[18:21], v[158:161], v[182:185], v[18:21]
	v_mfma_f32_16x16x32_bf16 v[6:9], v[150:153], v[190:193], v[6:9]
	v_mfma_f32_16x16x32_bf16 v[2:5], v[158:161], v[190:193], v[2:5]
	s_setprio 0
	s_barrier
	s_add_u32 s25, s25, 0x100
	s_addc_u32 s60, s60, 0
	s_cmp_ge_i32 s61, s59
	s_mov_b64 s[22:23], s[36:37]
	s_mov_b32 s44, s61
	s_cbranch_scc0 .LBB0_662
	s_and_b64 vcc, exec, s[14:15]
	s_cbranch_vccz .LBB0_665
	s_barrier

; #define PG8_STAGE(bufoff, gbase, voff) do { _Pragma("unroll") for (int _i = 0; _i < 2; ++_i) \
;         __builtin_amdgcn_global_load_lds((const unsigned*)((const char*)(gbase) + (voff)[_i]), (LAS unsigned*)(lds + (bufoff) + ldsw + _i * 8192), 16, 0, 0); } while (0)
; #define PG8_LDA(dst, b, h) do { _Pragma("unroll") for (int m = 0; m < 4; ++m) _Pragma("unroll") for (int k = 0; k < 2; ++k) dst[m][k] = *(const LAS bf16x8*)(lds + PG8_SA(b, h) + aoff + m * 2048 + k * 1024); } while (0)
; #define PG8_LDB(dst, b, h) do { _Pragma("unroll") for (int n = 0; n < 2; ++n) _Pragma("unroll") for (int k = 0; k < 2; ++k) dst[n][k] = *(const LAS bf16x8*)(lds + PG8_SB(b, h) + boff + n * 2048 + k * 1024); } while (0)
; #define PG8_MMA(ai, bj, At, Bt) do { __builtin_amdgcn_s_setprio(1); _Pragma("unroll") for (int m = 0; m < 4; ++m) _Pragma("unroll") for (int n = 0; n < 2; ++n) _Pragma("unroll") for (int k = 0; k < 2; ++k) \
;         acc[ai][bj][m][n] = __builtin_amdgcn_mfma_f32_16x16x32_bf16(Bt[n][k], At[m][k], acc[ai][bj][m][n], 0, 0, 0); __builtin_amdgcn_s_setprio(0); } while (0)
; #define PG8_WAIT_V(n) asm volatile("s_waitcnt vmcnt(" #n ")" ::: "memory")
; #define PG8_WAIT_L(n) asm volatile("s_waitcnt lgkmcnt(" #n ")" ::: "memory")
; #define PG8_BAR __builtin_amdgcn_s_barrier()
; #define PG8_SCHED __builtin_amdgcn_sched_barrier(0)
; template <class Epi, class Sched>
; __device__ __forceinline__ void gemm_phase(LAS unsigned char* lds, const int lda, const int ldb, const Sched& S, const Epi& E) {
;     ...
;             PG8_LDB(B0, 0, 0); PG8_LDB(B1, 0, 1); PG8_SCHED; PG8_LDA(At, 0, 0); PG8_STAGE(PG8_SA(1, 1), a1 + hstepA, voffA);
;             PG8_WAIT_V(8); PG8_WAIT_L(0); PG8_BAR; PG8_MMA(0, 0, At, B0); PG8_MMA(0, 1, At, B1); PG8_BAR; PG8_SCHED;
;             PG8_LDA(At, 0, 1); PG8_STAGE(PG8_SB(0, 0), b2, voffB); PG8_STAGE(PG8_SB(0, 1), b2 + hstepB, voffB); PG8_STAGE(PG8_SA(0, 0), a2, voffA);
;             PG8_WAIT_V(8); PG8_WAIT_L(0); PG8_BAR; PG8_MMA(1, 0, At, B0); PG8_MMA(1, 1, At, B1); PG8_BAR; PG8_SCHED;
.LBB0_802:
	s_add_u32 s36, s22, 0x100
	s_addc_u32 s37, s23, 0
	s_add_i32 s56, 0, 0x10000
	s_cmp_eq_u32 s25, 12
	s_cselect_b32 s47, s19, s37
	s_cselect_b32 s46, s18, s36
	v_add_u32_e32 v148, s56, v151
	s_cselect_b32 s45, s21, s24
	s_cselect_b32 s44, s20, s17
	s_add_i32 s57, 0, 0x14000
	ds_read_b128 v[140:143], v148
	ds_read_b128 v[144:147], v148 offset:1024
	ds_read_b128 v[154:157], v148 offset:2048
	ds_read_b128 v[158:161], v148 offset:3072
	v_add_u32_e32 v148, s57, v151
	ds_read_b128 v[162:165], v148
	ds_read_b128 v[166:169], v148 offset:1024
	ds_read_b128 v[170:173], v148 offset:2048
	ds_read_b128 v[174:177], v148 offset:3072
	v_lshl_add_u64 v[148:149], s[22:23], 0, v[136:137]
	s_add_i32 m0, s29, 0xc000
	ds_read_b128 v[178:181], v153
	ds_read_b128 v[182:185], v153 offset:1024
	ds_read_b128 v[186:189], v153 offset:2048
	ds_read_b128 v[190:193], v153 offset:3072
	ds_read_b128 v[206:209], v153 offset:4096
	ds_read_b128 v[210:213], v153 offset:5120
	ds_read_b128 v[214:217], v153 offset:6144
	ds_read_b128 v[218:221], v153 offset:7168
	global_load_lds_dwordx4 v[148:149], off
	v_lshl_add_u64 v[148:149], s[22:23], 0, v[138:139]
	s_add_i32 m0, s29, 0xe000
	s_nop 0
	global_load_lds_dwordx4 v[148:149], off
	s_waitcnt vmcnt(8)
	s_waitcnt lgkmcnt(0)
	s_barrier
	s_setprio 1
	s_waitcnt lgkmcnt(0)
	v_mfma_f32_16x16x32_bf16 v[126:129], v[140:143], v[178:181], v[126:129]
	v_mfma_f32_16x16x32_bf16 v[122:125], v[154:157], v[178:181], v[122:125]
	v_mfma_f32_16x16x32_bf16 v[110:113], v[140:143], v[186:189], v[110:113]
	v_mfma_f32_16x16x32_bf16 v[106:109], v[154:157], v[186:189], v[106:109]
	v_mfma_f32_16x16x32_bf16 v[94:97], v[140:143], v[206:209], v[94:97]
	v_mfma_f32_16x16x32_bf16 v[90:93], v[154:157], v[206:209], v[90:93]
	v_mfma_f32_16x16x32_bf16 v[78:81], v[140:143], v[214:217], v[78:81]
	v_mfma_f32_16x16x32_bf16 v[74:77], v[154:157], v[214:217], v[74:77]
	v_mfma_f32_16x16x32_bf16 v[126:129], v[144:147], v[182:185], v[126:129]
	v_mfma_f32_16x16x32_bf16 v[122:125], v[158:161], v[182:185], v[122:125]
	v_mfma_f32_16x16x32_bf16 v[110:113], v[144:147], v[190:193], v[110:113]
	v_mfma_f32_16x16x32_bf16 v[106:109], v[158:161], v[190:193], v[106:109]
	v_mfma_f32_16x16x32_bf16 v[94:97], v[144:147], v[210:213], v[94:97]
	v_mfma_f32_16x16x32_bf16 v[90:93], v[158:161], v[210:213], v[90:93]
	v_mfma_f32_16x16x32_bf16 v[78:81], v[144:147], v[218:221], v[78:81]
	v_mfma_f32_16x16x32_bf16 v[74:77], v[158:161], v[218:221], v[74:77]
	v_mfma_f32_16x16x32_bf16 v[118:121], v[162:165], v[178:181], v[118:121]
	v_mfma_f32_16x16x32_bf16 v[114:117], v[170:173], v[178:181], v[114:117]
	v_mfma_f32_16x16x32_bf16 v[102:105], v[162:165], v[186:189], v[102:105]
	v_mfma_f32_16x16x32_bf16 v[98:101], v[170:173], v[186:189], v[98:101]
	v_mfma_f32_16x16x32_bf16 v[86:89], v[162:165], v[206:209], v[86:89]
	v_mfma_f32_16x16x32_bf16 v[82:85], v[170:173], v[206:209], v[82:85]
	v_mfma_f32_16x16x32_bf16 v[70:73], v[162:165], v[214:217], v[70:73]
	v_mfma_f32_16x16x32_bf16 v[66:69], v[170:173], v[214:217], v[66:69]
	v_mfma_f32_16x16x32_bf16 v[118:121], v[166:169], v[182:185], v[118:121]
	v_mfma_f32_16x16x32_bf16 v[114:117], v[174:177], v[182:185], v[114:117]
	v_mfma_f32_16x16x32_bf16 v[102:105], v[166:169], v[190:193], v[102:105]
	v_mfma_f32_16x16x32_bf16 v[98:101], v[174:177], v[190:193], v[98:101]
	v_mfma_f32_16x16x32_bf16 v[86:89], v[166:169], v[210:213], v[86:89]
	v_mfma_f32_16x16x32_bf16 v[82:85], v[174:177], v[210:213], v[82:85]
	v_mfma_f32_16x16x32_bf16 v[70:73], v[166:169], v[218:221], v[70:73]
	v_mfma_f32_16x16x32_bf16 v[66:69], v[174:177], v[218:221], v[66:69]
	s_setprio 0
	s_barrier
	s_add_i32 s22, s56, s28
	v_lshl_add_u64 v[148:149], s[44:45], 0, v[0:1]
	s_mov_b32 m0, s22
	ds_read_b128 v[178:181], v153 offset:16384
	ds_read_b128 v[182:185], v153 offset:17408
	ds_read_b128 v[186:189], v153 offset:18432
	ds_read_b128 v[190:193], v153 offset:19456
	ds_read_b128 v[206:209], v153 offset:20480
	ds_read_b128 v[210:213], v153 offset:21504
	ds_read_b128 v[214:217], v153 offset:22528
	ds_read_b128 v[218:221], v153 offset:23552
	global_load_lds_dwordx4 v[148:149], off
	s_add_i32 m0, s22, 0x2000
	s_add_u32 s22, s44, 0x40000
	v_lshl_add_u64 v[222:223], s[44:45], 0, v[134:135]
	s_addc_u32 s23, s45, 0
	s_add_i32 s56, s57, s28
	global_load_lds_dwordx4 v[222:223], off
	v_lshl_add_u64 v[224:225], s[22:23], 0, v[0:1]
	s_mov_b32 m0, s56
	v_lshl_add_u64 v[240:241], s[46:47], 0, v[132:133]
	global_load_lds_dwordx4 v[224:225], off
	v_lshl_add_u64 v[224:225], s[22:23], 0, v[134:135]
	s_add_i32 m0, s56, 0x2000
	s_nop 0
	global_load_lds_dwordx4 v[224:225], off
	v_lshl_add_u64 v[224:225], s[46:47], 0, v[130:131]
	s_mov_b32 m0, s29
	s_nop 0
	global_load_lds_dwordx4 v[224:225], off
	s_mov_b32 m0, s33
	s_nop 0
	global_load_lds_dwordx4 v[240:241], off
	s_waitcnt vmcnt(8)
	s_waitcnt lgkmcnt(0)
	s_barrier
; #define PG8_STAGE(bufoff, gbase, voff) do { _Pragma("unroll") for (int _i = 0; _i < 2; ++_i) \
;         __builtin_amdgcn_global_load_lds((const unsigned*)((const char*)(gbase) + (voff)[_i]), (LAS unsigned*)(lds + (bufoff) + ldsw + _i * 8192), 16, 0, 0); } while (0)
; #define PG8_LDA(dst, b, h) do { _Pragma("unroll") for (int m = 0; m < 4; ++m) _Pragma("unroll") for (int k = 0; k < 2; ++k) dst[m][k] = *(const LAS bf16x8*)(lds + PG8_SA(b, h) + aoff + m * 2048 + k * 1024); } while (0)
; #define PG8_LDB(dst, b, h) do { _Pragma("unroll") for (int n = 0; n < 2; ++n) _Pragma("unroll") for (int k = 0; k < 2; ++k) dst[n][k] = *(const LAS bf16x8*)(lds + PG8_SB(b, h) + boff + n * 2048 + k * 1024); } while (0)
; #define PG8_MMA(ai, bj, At, Bt) do { __builtin_amdgcn_s_setprio(1); _Pragma("unroll") for (int m = 0; m < 4; ++m) _Pragma("unroll") for (int n = 0; n < 2; ++n) _Pragma("unroll") for (int k = 0; k < 2; ++k) \
;         acc[ai][bj][m][n] = __builtin_amdgcn_mfma_f32_16x16x32_bf16(Bt[n][k], At[m][k], acc[ai][bj][m][n], 0, 0, 0); __builtin_amdgcn_s_setprio(0); } while (0)
; #define PG8_WAIT_V(n) asm volatile("s_waitcnt vmcnt(" #n ")" ::: "memory")
; #define PG8_WAIT_L(n) asm volatile("s_waitcnt lgkmcnt(" #n ")" ::: "memory")
; #define PG8_BAR __builtin_amdgcn_s_barrier()
; #define PG8_SCHED __builtin_amdgcn_sched_barrier(0)
; template <class Epi, class Sched>
; __device__ __forceinline__ void gemm_phase(LAS unsigned char* lds, const int lda, const int ldb, const Sched& S, const Epi& E) {
;     ...
;             PG8_WAIT_V(8); PG8_WAIT_L(0); PG8_BAR; PG8_MMA(1, 0, At, B0); PG8_MMA(1, 1, At, B1); PG8_BAR; PG8_SCHED;
;             PG8_LDB(B0, 1, 0); PG8_LDB(B1, 1, 1); PG8_SCHED; PG8_LDA(At, 1, 0); PG8_STAGE(PG8_SA(0, 1), a2 + hstepA, voffA);
;             PG8_WAIT_V(8); PG8_WAIT_L(0); PG8_BAR; PG8_MMA(0, 0, At, B0); PG8_MMA(0, 1, At, B1); PG8_BAR; PG8_SCHED;
	s_setprio 1
	s_waitcnt lgkmcnt(0)
	v_mfma_f32_16x16x32_bf16 v[62:65], v[140:143], v[178:181], v[62:65]
	v_mfma_f32_16x16x32_bf16 v[58:61], v[154:157], v[178:181], v[58:61]
	v_mfma_f32_16x16x32_bf16 v[46:49], v[140:143], v[186:189], v[46:49]
	v_mfma_f32_16x16x32_bf16 v[42:45], v[154:157], v[186:189], v[42:45]
	v_mfma_f32_16x16x32_bf16 v[30:33], v[140:143], v[206:209], v[30:33]
	v_mfma_f32_16x16x32_bf16 v[26:29], v[154:157], v[206:209], v[26:29]
	v_mfma_f32_16x16x32_bf16 v[14:17], v[140:143], v[214:217], v[14:17]
	v_mfma_f32_16x16x32_bf16 v[10:13], v[154:157], v[214:217], v[10:13]
	v_mfma_f32_16x16x32_bf16 v[62:65], v[144:147], v[182:185], v[62:65]
	v_mfma_f32_16x16x32_bf16 v[58:61], v[158:161], v[182:185], v[58:61]
	v_mfma_f32_16x16x32_bf16 v[46:49], v[144:147], v[190:193], v[46:49]
	v_mfma_f32_16x16x32_bf16 v[42:45], v[158:161], v[190:193], v[42:45]
	v_mfma_f32_16x16x32_bf16 v[30:33], v[144:147], v[210:213], v[30:33]
	v_mfma_f32_16x16x32_bf16 v[26:29], v[158:161], v[210:213], v[26:29]
	v_mfma_f32_16x16x32_bf16 v[14:17], v[144:147], v[218:221], v[14:17]
	v_mfma_f32_16x16x32_bf16 v[10:13], v[158:161], v[218:221], v[10:13]
	v_mfma_f32_16x16x32_bf16 v[54:57], v[162:165], v[178:181], v[54:57]
	v_mfma_f32_16x16x32_bf16 v[50:53], v[170:173], v[178:181], v[50:53]
	v_mfma_f32_16x16x32_bf16 v[38:41], v[162:165], v[186:189], v[38:41]
	v_mfma_f32_16x16x32_bf16 v[34:37], v[170:173], v[186:189], v[34:37]
	v_mfma_f32_16x16x32_bf16 v[22:25], v[162:165], v[206:209], v[22:25]
	v_mfma_f32_16x16x32_bf16 v[18:21], v[170:173], v[206:209], v[18:21]
	v_mfma_f32_16x16x32_bf16 v[6:9], v[162:165], v[214:217], v[6:9]
	v_mfma_f32_16x16x32_bf16 v[2:5], v[170:173], v[214:217], v[2:5]
	v_mfma_f32_16x16x32_bf16 v[54:57], v[166:169], v[182:185], v[54:57]
	v_mfma_f32_16x16x32_bf16 v[50:53], v[174:177], v[182:185], v[50:53]
	v_mfma_f32_16x16x32_bf16 v[38:41], v[166:169], v[190:193], v[38:41]
	v_mfma_f32_16x16x32_bf16 v[34:37], v[174:177], v[190:193], v[34:37]
	v_mfma_f32_16x16x32_bf16 v[22:25], v[166:169], v[210:213], v[22:25]
	v_mfma_f32_16x16x32_bf16 v[18:21], v[174:177], v[210:213], v[18:21]
	v_mfma_f32_16x16x32_bf16 v[6:9], v[166:169], v[218:221], v[6:9]
	v_mfma_f32_16x16x32_bf16 v[2:5], v[174:177], v[218:221], v[2:5]
	s_setprio 0
	s_barrier
	s_add_i32 s56, 0, 0x18000
	s_add_i32 s57, 0, 0x1c000
	v_add_u32_e32 v158, s56, v151
	v_add_u32_e32 v174, s57, v151
	ds_read_b128 v[140:143], v158
	ds_read_b128 v[144:147], v158 offset:1024
	ds_read_b128 v[154:157], v158 offset:2048
	ds_read_b128 v[158:161], v158 offset:3072
	ds_read_b128 v[162:165], v174
	ds_read_b128 v[166:169], v174 offset:1024
	ds_read_b128 v[170:173], v174 offset:2048
	ds_read_b128 v[174:177], v174 offset:3072
	s_add_u32 s22, s46, 0x190000
	s_addc_u32 s23, s47, 0
	s_mov_b32 m0, s48
	v_lshl_add_u64 v[242:243], s[22:23], 0, v[130:131]
	ds_read_b128 v[178:181], v153 offset:32768
	ds_read_b128 v[182:185], v153 offset:33792
	ds_read_b128 v[186:189], v153 offset:34816
	ds_read_b128 v[190:193], v153 offset:35840
	ds_read_b128 v[206:209], v153 offset:36864
	ds_read_b128 v[210:213], v153 offset:37888
	ds_read_b128 v[214:217], v153 offset:38912
	ds_read_b128 v[218:221], v153 offset:39936
	global_load_lds_dwordx4 v[242:243], off
	v_lshl_add_u64 v[242:243], s[22:23], 0, v[132:133]
	s_mov_b32 m0, s49
	s_nop 0
	global_load_lds_dwordx4 v[242:243], off
	s_waitcnt vmcnt(8)
	s_waitcnt lgkmcnt(0)
	s_barrier
	s_setprio 1
	s_waitcnt lgkmcnt(0)
	v_mfma_f32_16x16x32_bf16 v[126:129], v[140:143], v[178:181], v[126:129]
	v_mfma_f32_16x16x32_bf16 v[122:125], v[154:157], v[178:181], v[122:125]
	v_mfma_f32_16x16x32_bf16 v[110:113], v[140:143], v[186:189], v[110:113]
	v_mfma_f32_16x16x32_bf16 v[106:109], v[154:157], v[186:189], v[106:109]
	v_mfma_f32_16x16x32_bf16 v[94:97], v[140:143], v[206:209], v[94:97]
	v_mfma_f32_16x16x32_bf16 v[90:93], v[154:157], v[206:209], v[90:93]
	v_mfma_f32_16x16x32_bf16 v[78:81], v[140:143], v[214:217], v[78:81]
	v_mfma_f32_16x16x32_bf16 v[74:77], v[154:157], v[214:217], v[74:77]
	v_mfma_f32_16x16x32_bf16 v[126:129], v[144:147], v[182:185], v[126:129]
	v_mfma_f32_16x16x32_bf16 v[122:125], v[158:161], v[182:185], v[122:125]
	v_mfma_f32_16x16x32_bf16 v[110:113], v[144:147], v[190:193], v[110:113]
	v_mfma_f32_16x16x32_bf16 v[106:109], v[158:161], v[190:193], v[106:109]
	v_mfma_f32_16x16x32_bf16 v[94:97], v[144:147], v[210:213], v[94:97]
	v_mfma_f32_16x16x32_bf16 v[90:93], v[158:161], v[210:213], v[90:93]
	v_mfma_f32_16x16x32_bf16 v[78:81], v[144:147], v[218:221], v[78:81]
	v_mfma_f32_16x16x32_bf16 v[74:77], v[158:161], v[218:221], v[74:77]
	v_mfma_f32_16x16x32_bf16 v[118:121], v[162:165], v[178:181], v[118:121]
	v_mfma_f32_16x16x32_bf16 v[114:117], v[170:173], v[178:181], v[114:117]
	v_mfma_f32_16x16x32_bf16 v[102:105], v[162:165], v[186:189], v[102:105]
	v_mfma_f32_16x16x32_bf16 v[98:101], v[170:173], v[186:189], v[98:101]
	v_mfma_f32_16x16x32_bf16 v[86:89], v[162:165], v[206:209], v[86:89]
	v_mfma_f32_16x16x32_bf16 v[82:85], v[170:173], v[206:209], v[82:85]
	v_mfma_f32_16x16x32_bf16 v[70:73], v[162:165], v[214:217], v[70:73]
	v_mfma_f32_16x16x32_bf16 v[66:69], v[170:173], v[214:217], v[66:69]
	v_mfma_f32_16x16x32_bf16 v[118:121], v[166:169], v[182:185], v[118:121]
	v_mfma_f32_16x16x32_bf16 v[114:117], v[174:177], v[182:185], v[114:117]
	v_mfma_f32_16x16x32_bf16 v[102:105], v[166:169], v[190:193], v[102:105]
	v_mfma_f32_16x16x32_bf16 v[98:101], v[174:177], v[190:193], v[98:101]
	v_mfma_f32_16x16x32_bf16 v[86:89], v[166:169], v[210:213], v[86:89]
	v_mfma_f32_16x16x32_bf16 v[82:85], v[174:177], v[210:213], v[82:85]
	v_mfma_f32_16x16x32_bf16 v[70:73], v[166:169], v[218:221], v[70:73]
	v_mfma_f32_16x16x32_bf16 v[66:69], v[174:177], v[218:221], v[66:69]
	s_setprio 0
	s_barrier
; #define PG8_STAGE(bufoff, gbase, voff) do { _Pragma("unroll") for (int _i = 0; _i < 2; ++_i) \
;         __builtin_amdgcn_global_load_lds((const unsigned*)((const char*)(gbase) + (voff)[_i]), (LAS unsigned*)(lds + (bufoff) + ldsw + _i * 8192), 16, 0, 0); } while (0)
; #define PG8_LDA(dst, b, h) do { _Pragma("unroll") for (int m = 0; m < 4; ++m) _Pragma("unroll") for (int k = 0; k < 2; ++k) dst[m][k] = *(const LAS bf16x8*)(lds + PG8_SA(b, h) + aoff + m * 2048 + k * 1024); } while (0)
; #define PG8_MMA(ai, bj, At, Bt) do { __builtin_amdgcn_s_setprio(1); _Pragma("unroll") for (int m = 0; m < 4; ++m) _Pragma("unroll") for (int n = 0; n < 2; ++n) _Pragma("unroll") for (int k = 0; k < 2; ++k) \
;         acc[ai][bj][m][n] = __builtin_amdgcn_mfma_f32_16x16x32_bf16(Bt[n][k], At[m][k], acc[ai][bj][m][n], 0, 0, 0); __builtin_amdgcn_s_setprio(0); } while (0)
; #define PG8_WAIT_V(n) asm volatile("s_waitcnt vmcnt(" #n ")" ::: "memory")
; #define PG8_WAIT_L(n) asm volatile("s_waitcnt lgkmcnt(" #n ")" ::: "memory")
; #define PG8_BAR __builtin_amdgcn_s_barrier()
; #define PG8_SCHED __builtin_amdgcn_sched_barrier(0)
; template <class Epi, class Sched>
; __device__ __forceinline__ void gemm_phase(LAS unsigned char* lds, const int lda, const int ldb, const Sched& S, const Epi& E) {
;     ...
;             PG8_LDA(At, 1, 1); PG8_STAGE(PG8_SB(1, 0), b3, voffB); PG8_STAGE(PG8_SB(1, 1), b3 + hstepB, voffB); PG8_STAGE(PG8_SA(1, 0), a3, voffA);
;             PG8_WAIT_V(8); PG8_WAIT_L(0); PG8_BAR; PG8_MMA(1, 0, At, B0); PG8_MMA(1, 1, At, B1); PG8_BAR; PG8_SCHED;
;         }
;         if (wr == 0) PG8_BAR;
	s_add_i32 s22, s56, s28
	v_lshl_add_u64 v[148:149], v[148:149], 0, s[82:83]
	s_mov_b32 m0, s22
	ds_read_b128 v[178:181], v153 offset:49152
	ds_read_b128 v[182:185], v153 offset:50176
	ds_read_b128 v[186:189], v153 offset:51200
	ds_read_b128 v[190:193], v153 offset:52224
	ds_read_b128 v[206:209], v153 offset:53248
	ds_read_b128 v[210:213], v153 offset:54272
	ds_read_b128 v[214:217], v153 offset:55296
	ds_read_b128 v[218:221], v153 offset:56320
	global_load_lds_dwordx4 v[148:149], off
	s_add_i32 m0, s22, 0x2000
	s_add_u32 s22, s44, 0x40080
	v_lshl_add_u64 v[148:149], v[222:223], 0, s[82:83]
	s_addc_u32 s23, s45, 0
	s_add_i32 s44, s57, s28
	global_load_lds_dwordx4 v[148:149], off
	v_lshl_add_u64 v[148:149], s[22:23], 0, v[0:1]
	s_mov_b32 m0, s44
	s_nop 0
	global_load_lds_dwordx4 v[148:149], off
	v_lshl_add_u64 v[148:149], s[22:23], 0, v[134:135]
	s_add_i32 m0, s44, 0x2000
	s_nop 0
	global_load_lds_dwordx4 v[148:149], off
	v_lshl_add_u64 v[148:149], v[224:225], 0, s[82:83]
	s_mov_b32 m0, s51
	s_nop 0
	global_load_lds_dwordx4 v[148:149], off
	v_lshl_add_u64 v[148:149], v[240:241], 0, s[82:83]
	s_mov_b32 m0, s52
	s_nop 0
	global_load_lds_dwordx4 v[148:149], off
	s_waitcnt vmcnt(8)
	s_waitcnt lgkmcnt(0)
	s_barrier
	s_setprio 1
	s_waitcnt lgkmcnt(0)
	v_mfma_f32_16x16x32_bf16 v[62:65], v[140:143], v[178:181], v[62:65]
	v_mfma_f32_16x16x32_bf16 v[58:61], v[154:157], v[178:181], v[58:61]
	v_mfma_f32_16x16x32_bf16 v[46:49], v[140:143], v[186:189], v[46:49]
	v_mfma_f32_16x16x32_bf16 v[42:45], v[154:157], v[186:189], v[42:45]
	v_mfma_f32_16x16x32_bf16 v[30:33], v[140:143], v[206:209], v[30:33]
	v_mfma_f32_16x16x32_bf16 v[26:29], v[154:157], v[206:209], v[26:29]
	v_mfma_f32_16x16x32_bf16 v[14:17], v[140:143], v[214:217], v[14:17]
	v_mfma_f32_16x16x32_bf16 v[10:13], v[154:157], v[214:217], v[10:13]
	v_mfma_f32_16x16x32_bf16 v[62:65], v[144:147], v[182:185], v[62:65]
	v_mfma_f32_16x16x32_bf16 v[58:61], v[158:161], v[182:185], v[58:61]
	v_mfma_f32_16x16x32_bf16 v[46:49], v[144:147], v[190:193], v[46:49]
	v_mfma_f32_16x16x32_bf16 v[42:45], v[158:161], v[190:193], v[42:45]
	v_mfma_f32_16x16x32_bf16 v[30:33], v[144:147], v[210:213], v[30:33]
	v_mfma_f32_16x16x32_bf16 v[26:29], v[158:161], v[210:213], v[26:29]
	v_mfma_f32_16x16x32_bf16 v[14:17], v[144:147], v[218:221], v[14:17]
	v_mfma_f32_16x16x32_bf16 v[10:13], v[158:161], v[218:221], v[10:13]
	v_mfma_f32_16x16x32_bf16 v[54:57], v[162:165], v[178:181], v[54:57]
	v_mfma_f32_16x16x32_bf16 v[50:53], v[170:173], v[178:181], v[50:53]
	v_mfma_f32_16x16x32_bf16 v[38:41], v[162:165], v[186:189], v[38:41]
	v_mfma_f32_16x16x32_bf16 v[34:37], v[170:173], v[186:189], v[34:37]
	v_mfma_f32_16x16x32_bf16 v[22:25], v[162:165], v[206:209], v[22:25]
	v_mfma_f32_16x16x32_bf16 v[18:21], v[170:173], v[206:209], v[18:21]
	v_mfma_f32_16x16x32_bf16 v[6:9], v[162:165], v[214:217], v[6:9]
	v_mfma_f32_16x16x32_bf16 v[2:5], v[170:173], v[214:217], v[2:5]
	v_mfma_f32_16x16x32_bf16 v[54:57], v[166:169], v[182:185], v[54:57]
	v_mfma_f32_16x16x32_bf16 v[50:53], v[174:177], v[182:185], v[50:53]
	v_mfma_f32_16x16x32_bf16 v[38:41], v[166:169], v[190:193], v[38:41]
	v_mfma_f32_16x16x32_bf16 v[34:37], v[174:177], v[190:193], v[34:37]
	v_mfma_f32_16x16x32_bf16 v[22:25], v[166:169], v[210:213], v[22:25]
	v_mfma_f32_16x16x32_bf16 v[18:21], v[174:177], v[210:213], v[18:21]
	v_mfma_f32_16x16x32_bf16 v[6:9], v[166:169], v[218:221], v[6:9]
	v_mfma_f32_16x16x32_bf16 v[2:5], v[174:177], v[218:221], v[2:5]
	s_setprio 0
	s_barrier
	s_add_i32 s25, s25, 2
	s_add_u32 s17, s17, 0x100
	s_addc_u32 s24, s24, 0
	s_cmp_gt_u32 s25, 13
	s_mov_b64 s[22:23], s[36:37]
	s_cbranch_scc0 .LBB0_802
	s_and_b64 vcc, exec, s[14:15]
	s_cbranch_vccz .LBB0_805
	s_barrier
